# P9 tail-part placement: split-K tail parts go to the owners of whole row panels ((pm mod 8) < 4) so the other 32 panels finish their final-norm exchange and output stores ~13 us early; stacked on v93
# baseline (speedup 1.0000x reference)
.LBB0_2087:
	s_cmp_lt_i32 s36, 10
	s_cselect_b64 s[4:5], -1, 0
	s_cmpk_eq_i32 s54, 0x100
	s_cselect_b64 s[2:3], -1, 0
	s_and_b64 s[0:1], s[0:1], s[2:3]
	s_and_b64 s[0:1], s[4:5], s[0:1]
	s_andn2_b64 vcc, exec, s[0:1]
	s_cbranch_vccnz .LBB0_2201
	s_bitcmp0_b32 s56, 5
	s_cselect_b64 s[14:15], -1, 0
	s_bitcmp1_b32 s56, 5
	v_readfirstlane_b32 s3, v0
	s_cbranch_scc0 .LBB0_2091
	s_cmpk_lt_u32 s56, 0x100
	s_cbranch_scc1 .LBB0_2092
	s_add_i32 s0, s56, 0xffffff00
	s_lshr_b32 s0, s0, 2
	s_add_i32 s72, s0, 64
	s_and_b32 s16, s56, 3
	s_cbranch_execz .LBB0_2093
	s_branch .LBB0_2094

.LBB0_2095:
	v_writelane_b32 v255, s4, 2
	s_andn2_b64 vcc, exec, s[0:1]
	s_nop 0
	v_writelane_b32 v255, s5, 3
	s_cbranch_vccnz .LBB0_2098
	s_ashr_i32 s1, s56, 3
	s_and_b32 s0, s56, 7
	s_lshr_b32 s2, s56, 7
	s_lshl_b32 s2, s2, 3
	s_or_b32 s2, s2, s0
	s_cmp_lt_i32 s1, 0
	s_cbranch_scc1 .LBB0_2099
	s_lshr_b32 s0, s2, 2
	s_add_i32 s72, s0, 64
	s_and_b32 s16, s56, 3
	s_cbranch_execz .LBB0_2100
	s_branch .LBB0_2105

.LBB0_2105:
	s_bfe_u32 s73, s56, 0x20003
	s_lshr_b32 s0, s56, 4
	s_and_b32 s0, s0, 4
	s_or_b32 s73, s73, s0
	s_mul_i32 s0, s73, 22
	s_lshr_b32 s1, s0, 3
	s_add_i32 s0, s0, 22
	s_lshr_b32 s4, s0, 3
	s_lshl_b32 s0, s1, 8
	s_sub_i32 s1, s4, s1
	s_lshl_b32 s74, s1, 1
	s_mov_b32 s1, 0

.LBB0_2108:
	s_add_u32 s0, s70, 0x10000
	v_writelane_b32 v254, s0, 45
	s_addc_u32 s0, s71, 0
	v_writelane_b32 v254, s0, 29
	s_add_u32 s0, s70, 0x14400
	v_writelane_b32 v255, s0, 15
	s_addc_u32 s0, s71, 0
	v_bfe_u32 v216, v0, 4, 2
	v_writelane_b32 v255, s0, 23
	s_add_u32 s0, s70, 0xd000
	v_lshlrev_b32_e32 v12, 4, v216
	v_lshlrev_b32_e32 v14, 2, v0
	v_writelane_b32 v255, s0, 21
	s_addc_u32 s0, s71, 0
	v_lshl_or_b32 v13, v1, 6, v12
	s_lshl_b32 s1, s4, 13
	v_and_b32_e32 v14, 32, v14
	v_writelane_b32 v255, s0, 17
	s_and_b32 s0, s5, 3
	v_bitop3_b32 v15, v13, s1, v14 bitop3:0xde
	v_lshlrev_b32_e32 v13, 6, v0
	s_movk_i32 s1, 0x3c0
	s_lshl_b32 s88, s4, 6
	s_lshl_b32 s89, s0, 5
	v_and_or_b32 v12, v13, s1, v12
	s_lshl_b32 s1, s0, 12
	s_add_u32 s44, s70, 0x1cc000
	s_mov_b64 s[46:47], 0x80
	v_bitop3_b32 v218, s1, v12, v14 bitop3:0xf6
	s_addc_u32 s45, s71, 0
	v_lshl_add_u64 v[12:13], v[2:3], 0, s[46:47]
	s_add_i32 m0, s78, 0x18000
	s_mov_b64 s[48:49], 0x58080
	s_waitcnt vmcnt(2)
	s_barrier
	global_load_lds_dwordx4 v[12:13], off
	v_lshl_add_u64 v[12:13], v[2:3], 0, s[48:49]
	s_add_i32 m0, s78, 0x1a000
	s_add_i32 s90, s78, 0x8000
	global_load_lds_dwordx4 v[12:13], off
	v_lshl_add_u64 v[12:13], v[4:5], 0, s[46:47]
	s_mov_b32 m0, s90
	s_add_i32 s91, s78, 0xa000
	global_load_lds_dwordx4 v[12:13], off
	v_lshl_add_u64 v[4:5], v[4:5], 0, s[48:49]
	s_mov_b32 m0, s91
	s_mov_b64 s[50:51], 0xb0080
	global_load_lds_dwordx4 v[4:5], off
	v_lshl_add_u64 v[4:5], v[2:3], 0, s[50:51]
	s_add_i32 m0, s78, 0x1c000
	s_mov_b64 s[52:53], 0x108080
	global_load_lds_dwordx4 v[4:5], off
	v_lshl_add_u64 v[2:3], v[2:3], 0, s[52:53]
	s_add_i32 m0, s78, 0x1e000
	s_add_i32 s92, 0, 0x20000
	global_load_lds_dwordx4 v[2:3], off
	s_lshl_b32 s0, s0, 2
	s_add_i32 s93, s92, s0
	s_cmpk_lt_u32 s3, 0x100
	s_cselect_b64 s[54:55], -1, 0
	s_ashr_i32 s8, s56, 3
	s_and_b32 s3, s56, 7
	s_lshr_b32 s9, s56, 7
	s_lshl_b32 s9, s9, 3
	s_or_b32 s96, s9, s3
	s_bfe_u32 s82, s56, 0x20003
	s_lshr_b32 s9, s56, 4
	s_and_b32 s9, s9, 4
	s_or_b32 s82, s82, s9
	s_add_i32 s9, s96, 0x100
	s_lshr_b32 s12, s9, 29
	s_mul_i32 s17, s82, 22
	s_add_i32 s12, s9, s12
	s_lshr_b32 s28, s17, 3
	s_add_i32 s17, s17, 22
	s_ashr_i32 s13, s12, 3
	s_and_b32 s12, s12, -8
	s_lshr_b32 s17, s17, 3
	s_lshr_b32 s3, s96, 2
	s_sub_i32 s9, s9, s12
	s_sub_i32 s17, s17, s28
	s_and_b32 s29, s56, 3
	s_add_i32 s3, s3, 64
	s_lshl_b32 s12, s9, 5
	s_lshl_b32 s40, s28, 8
	s_lshl_b32 s83, s17, 1
	s_cmp_lt_i32 s9, 0
	s_mul_i32 s9, s9, 33
	s_cselect_b32 s9, s9, s12
	s_add_i32 s9, s9, s13
	s_ashr_i32 s12, s9, 31
	s_lshr_b32 s12, s12, 27
	s_add_i32 s12, s9, s12
	s_ashr_i32 s13, s12, 5
	s_and_b32 s12, s12, 0xffe0
	s_sub_i32 s9, s9, s12
	s_bfe_i32 s12, s9, 0x80000
	s_bfe_u32 s12, s12, 0x3000c
	s_add_i32 s12, s9, s12
	s_bfe_i32 s17, s12, 0x80000
	s_and_b32 s12, s12, 0xf8
	s_sub_i32 s9, s9, s12
	v_cndmask_b32_e64 v2, 0, -1, s[14:15]
	s_lshl_b32 s13, s13, 3
	s_sext_i32_i16 s17, s17
	s_sext_i32_i8 s9, s9
	v_readfirstlane_b32 s94, v2
	s_add_i32 s13, s13, s9
	s_ashr_i32 s9, s17, 3
	v_add_u32_e32 v2, v6, v7
	s_waitcnt vmcnt(6)
	s_cmp_lt_i32 s8, 0
	v_and_b32_e32 v2, 0xe0, v2
	s_movk_i32 s4, 0x100
	s_cselect_b32 s13, s13, s3
	s_cselect_b32 s28, s9, s29
	v_add3_u32 v198, v8, v2, v9
	s_add_i32 s86, 0, 0x10000
	s_add_i32 s87, 0, 0x14000
	v_mbcnt_lo_u32_b32 v2, -1, 0
	v_or_b32_e32 v217, s88, v1
	v_cmp_eq_u32_e64 s[0:1], 0, v0
	v_cmp_eq_u32_e64 s[10:11], 0, v216
	v_cmp_gt_u32_e64 s[4:5], s4, v0
	v_or_b32_e32 v219, v11, v216
	v_add_u32_e32 v220, s92, v10
	v_cmp_eq_u32_e64 s[6:7], 0, v186
	v_mul_i32_i24_e32 v221, -12, v0
	v_writelane_b32 v255, s29, 19
	s_mov_b64 s[56:57], s[40:41]
	v_lshl_or_b32 v222, v216, 3, s89
	v_mov_b32_e32 v199, v197
	v_add_u32_e32 v223, s86, v218
	v_add_u32_e32 v224, s87, v218
	v_add_u32_e32 v225, 0, v15
	v_mov_b32_e32 v226, 0x358637bd
	v_mbcnt_hi_u32_b32 v227, -1, v2
	s_mov_b32 s3, 0
	s_barrier
	s_branch .LBB0_2111
